# v33 with hgrn head start of 6 chunks (stop index 5, was 7) during gdnpre
# speedup vs baseline: 1.0070x; 1.0070x over previous
.Lhs_p3:
	s_movk_i32 s101, 5
	s_cmp_lt_u32 s62, 64
	s_cbranch_scc1 .Lhs_done
	s_sub_u32 s64, s62, 64
	s_movk_i32 s75, 0xc0
